# lambda reduction: xor-1/2/4/8 butterfly steps via DPP instead of ds_bpermute round trips (same operand order)
# speedup vs baseline: 1.0008x; 1.0008x over previous
.LBB0_561:
	v_readlane_b32 s0, v241, 21
	v_readlane_b32 s48, v241, 37
	v_readlane_b32 s1, v241, 22
	v_readlane_b32 s2, v241, 23
	v_readlane_b32 s3, v241, 24
	v_readlane_b32 s4, v241, 25
	v_readlane_b32 s5, v241, 26
	v_readlane_b32 s6, v241, 27
	v_readlane_b32 s7, v241, 28
	v_readlane_b32 s49, v241, 38
	v_lshlrev_b32_e32 v128, 2, v147
	v_readlane_b32 s14, v241, 35
	v_readlane_b32 s15, v241, 36
	v_readlane_b32 s50, v241, 39
	v_readlane_b32 s51, v241, 40
	v_readlane_b32 s52, v241, 41
	v_readlane_b32 s53, v241, 42
	v_readlane_b32 s54, v241, 43
	v_readlane_b32 s55, v241, 44
	s_mov_b64 s[0:1], s[48:49]
	s_nop 0
	s_mov_b64 s[2:3], s[50:51]
	s_mov_b64 s[4:5], s[52:53]
	s_nop 0
	s_nop 0
	s_nop 0
	v_cmp_lt_i32_e32 vcc, v202, v1
	s_cmpk_gt_i32 s72, 0xff
	v_readlane_b32 s8, v241, 29
	v_cndmask_b32_e32 v6, v196, v202, vcc
	v_lshlrev_b32_e32 v154, 2, v6
	v_cmp_lt_i32_e32 vcc, v201, v1
	v_readlane_b32 s9, v241, 30
	v_readlane_b32 s10, v241, 31
	v_cndmask_b32_e32 v8, v196, v201, vcc
	v_lshlrev_b32_e32 v155, 2, v8
	v_cmp_lt_i32_e32 vcc, v200, v1
	v_readlane_b32 s11, v241, 32
	v_readlane_b32 s12, v241, 33
	v_readlane_b32 s13, v241, 34
	v_readlane_b32 s56, v241, 45
	v_readlane_b32 s57, v241, 46
	v_readlane_b32 s58, v241, 47
	v_readlane_b32 s59, v241, 48
	v_readlane_b32 s60, v241, 49
	v_readlane_b32 s61, v241, 50
	v_readlane_b32 s62, v241, 51
	v_readlane_b32 s63, v241, 52
	s_mov_b64 s[6:7], s[54:55]
	s_waitcnt vmcnt(0)
	v_mov_b32_e32 v2, v244
	v_mov_b32_e32 v3, v245
	v_mov_b32_e32 v4, v246
	v_mov_b32_e32 v5, v247
	v_cndmask_b32_e32 v8, v196, v200, vcc
	v_lshlrev_b32_e32 v156, 2, v8
	v_mul_f32_e32 v6, v2, v3
	v_mul_f32_e32 v7, v4, v5
	s_nop 1
	v_mov_b32_dpp v6, v6 quad_perm:[1,0,3,2] row_mask:0xf bank_mask:0xf
	v_mov_b32_dpp v7, v7 quad_perm:[1,0,3,2] row_mask:0xf bank_mask:0xf
	v_fmac_f32_e32 v6, v2, v3
	v_fmac_f32_e32 v7, v4, v5
	s_nop 1
	v_add_f32_dpp v6, v6, v6 quad_perm:[2,3,0,1] row_mask:0xf bank_mask:0xf
	v_add_f32_dpp v7, v7, v7 quad_perm:[2,3,0,1] row_mask:0xf bank_mask:0xf
	s_nop 1
	v_add_f32_dpp v6, v6, v6 row_half_mirror row_mask:0xf bank_mask:0xf
	v_add_f32_dpp v7, v7, v7 row_half_mirror row_mask:0xf bank_mask:0xf
	s_nop 1
	v_add_f32_dpp v2, v6, v6 row_mirror row_mask:0xf bank_mask:0xf
	v_add_f32_dpp v3, v7, v7 row_mirror row_mask:0xf bank_mask:0xf
	v_cmp_lt_i32_e32 vcc, v199, v1
	s_nop 1
	v_cndmask_b32_e32 v4, v196, v199, vcc
	v_lshlrev_b32_e32 v157, 2, v4
	v_cmp_lt_i32_e32 vcc, v198, v1
	s_nop 1
	v_cndmask_b32_e32 v4, v196, v198, vcc
	v_lshlrev_b32_e32 v158, 2, v4
	s_nop 0
	ds_bpermute_b32 v4, v158, v2
	ds_bpermute_b32 v5, v158, v3
	v_cmp_lt_i32_e32 vcc, v197, v1
	s_nop 1
	v_cndmask_b32_e32 v1, v196, v197, vcc
	v_lshlrev_b32_e32 v159, 2, v1
	s_waitcnt lgkmcnt(1)
	v_add_f32_e32 v1, v2, v4
	s_waitcnt lgkmcnt(0)
	v_add_f32_e32 v2, v3, v5
	ds_bpermute_b32 v3, v159, v1
	ds_bpermute_b32 v4, v159, v2
	s_cbranch_scc1 .LBB0_624
	v_writelane_b32 v240, s34, 13
	s_lshr_b32 s33, s21, 16
	s_and_b32 s0, s21, 0xffff
	v_writelane_b32 v240, s35, 14
	v_writelane_b32 v240, s86, 9
	s_waitcnt lgkmcnt(1)
	v_add_f32_e32 v1, v1, v3
	s_waitcnt lgkmcnt(0)
	v_add_f32_e32 v2, v2, v4
	s_add_u32 s28, s94, 0x4000
	v_writelane_b32 v240, s87, 10
	v_mul_f32_e32 v1, 0x3fb8aa3b, v1
	v_mul_f32_e32 v2, 0x3fb8aa3b, v2
	s_addc_u32 s29, s95, 0
	v_writelane_b32 v240, s96, 15
	v_exp_f32_e32 v1, v1
	v_exp_f32_e32 v2, v2
	s_add_u32 s1, s94, 0x1a400000
	v_writelane_b32 v240, s97, 16
	v_writelane_b32 v241, s1, 21
	s_addc_u32 s1, s95, 0
	v_writelane_b32 v240, s1, 17
	s_add_u32 s1, s94, 0x5000
	s_mov_b32 s2, 0x10400
	v_add_u32_e32 v3, 0x200, v146
	v_writelane_b32 v240, s1, 18
	s_addc_u32 s1, s95, 0
	s_addk_i32 s2, 0x100
	v_lshrrev_b32_e32 v163, 4, v3
	v_and_b32_e32 v6, 0x7f0, v3
	v_or_b32_e32 v3, 0x400, v146
	v_sub_f32_e32 v1, v1, v2
	v_mov_b32_e32 v2, s2
	s_movk_i32 s2, 0x7f0
	v_lshrrev_b32_e32 v164, 4, v3
	v_mov_b32_e32 v3, 0x400
	v_bitop3_b32 v7, v146, s2, v3 bitop3:0xc8
	s_bfe_u32 s2, s64, 0x10006
	v_add_u32_e32 v3, 0x600, v146
	v_lshrrev_b32_e32 v9, 5, v147
	s_lshl_b32 s4, s2, 3
	v_add_f32_e32 v160, 0x3e4ccccd, v1
	v_and_b32_e32 v1, 15, v146
	s_movk_i32 s3, 0x810
	v_lshrrev_b32_e32 v165, 4, v3
	v_and_b32_e32 v8, 0xff0, v3
	v_or_b32_e32 v3, s4, v9
	v_lshrrev_b32_e32 v12, 1, v146
	v_lshlrev_b32_e32 v13, 1, v146
	v_writelane_b32 v240, s1, 19
	s_lshr_b32 s1, s64, 7
	v_mad_u32_u24 v4, v1, s3, v2
	v_mad_u32_u24 v11, v3, s3, v2
	v_and_b32_e32 v2, 19, v146
	v_and_b32_e32 v12, 4, v12
	v_and_b32_e32 v13, 8, v13
	s_lshl_b32 s16, s1, 5
	s_lshr_b32 s17, s64, 8
	v_or3_b32 v2, v2, v12, v13
	v_writelane_b32 v240, s4, 20
	v_lshlrev_b32_e32 v2, 4, v2
	s_movk_i32 s4, 0x410
	s_cmpk_lt_u32 s64, 0x100
	v_mad_u32_u24 v166, v3, s4, v2
	v_lshrrev_b32_e32 v2, 4, v147
	v_lshrrev_b32_e32 v3, 3, v147
	s_cselect_b32 s4, 0x8200, 0
	v_lshlrev_b32_e32 v130, 4, v1
	v_lshl_or_b32 v2, s20, 3, v2
	v_lshl_or_b32 v169, s20, 4, v3
	v_mul_u32_u24_e32 v1, 0x410, v1
	s_addk_i32 s4, 0x100
	v_and_b32_e32 v12, 7, v146
	v_lshl_add_u32 v170, v2, 4, v1
	v_lshlrev_b32_e32 v1, 4, v169
	s_cmpk_gt_u32 s64, 0xff
	v_writelane_b32 v240, s4, 21
	s_cselect_b64 s[4:5], -1, 0
	v_mad_u32_u24 v172, v12, s3, v1
	v_bfe_u32 v1, v0, 10, 10
	v_bfe_u32 v0, v0, 20, 10
	s_mov_b32 s21, 0
	v_writelane_b32 v240, s4, 22
	s_lshl_b32 s68, s0, 8
	v_mad_u32_u24 v173, v0, s0, v1
	s_and_b32 s0, s64, 0xffffffc0
	v_writelane_b32 v240, s5, 23
	v_or_b32_e32 v0, s0, v147
	s_lshl_b64 s[4:5], s[20:21], 14
	s_and_b32 s0, 64, s64
	v_writelane_b32 v240, s4, 24
	s_cmp_eq_u32 s2, 0
	s_cselect_b64 s[2:3], -1, 0
	v_writelane_b32 v240, s5, 25
	v_writelane_b32 v240, s2, 26
	s_cmp_lg_u32 s0, 0
	v_mov_b32_e32 v131, 0
	v_writelane_b32 v240, s3, 27
	s_cselect_b64 s[2:3], -1, 0
	s_lshl_b32 s0, s1, 14
	v_mov_b32_e32 v3, v131
	v_writelane_b32 v240, s2, 28
	s_addk_i32 s0, 0x100
	v_lshlrev_b64 v[2:3], 11, v[2:3]
	v_writelane_b32 v240, s3, 29
	v_lshl_add_u32 v174, v147, 2, s0
	v_readlane_b32 s0, v241, 37
	v_and_b32_e32 v161, 31, v146
	v_lshl_add_u64 v[2:3], s[42:43], 0, v[2:3]
	v_writelane_b32 v240, s17, 30
	s_sub_i32 s0, 0, s17
	v_lshl_add_u64 v[132:133], s[66:67], 0, v[130:131]
	v_or_b32_e32 v10, s16, v161
	v_lshl_add_u64 v[134:135], v[2:3], 0, v[130:131]
	v_lshlrev_b32_e32 v130, 4, v12
	v_readlane_b32 s2, v241, 39
	v_readlane_b32 s3, v241, 40
	v_writelane_b32 v240, s0, 31
	s_mov_b32 s0, 0x20c30
	v_and_b32_e32 v5, 0x3f0, v146
	v_lshlrev_b32_e32 v10, 4, v10
	v_lshl_add_u64 v[136:137], s[40:41], 0, v[130:131]
	v_mul_i32_i24_e32 v171, -8, v9
	v_add_u32_e32 v138, 0x8000, v0
	v_add_u32_e32 v140, 0x8200, v0
	v_lshlrev_b32_e32 v0, 2, v9
	v_lshlrev_b32_e32 v130, 4, v9
	v_readlane_b32 s6, v241, 43
	v_readlane_b32 s7, v241, 44
	s_add_i32 s71, s0, 0x100
	s_mov_b32 s40, 0xc2000000
	s_mov_b32 s42, -2.0
	s_mov_b32 s44, 0xc2080000
	s_mov_b32 s46, -4.0
	s_mov_b32 s48, 0xc2100000
	s_mov_b32 s50, 0xc0c00000
	s_mov_b32 s52, 0xc2180000
	s_mov_b32 s54, 0xc1800000
	s_mov_b32 s56, 0xc2400000
	s_mov_b32 s58, 0xc1900000
	s_mov_b32 s60, 0xc2480000
	s_mov_b32 s62, 0xc1a00000
	s_mov_b32 s64, 0xc2500000
	s_mov_b32 s66, 0xc1b00000
	s_mov_b32 s82, 0xc2580000
	s_mov_b32 s84, 2.0
	s_mov_b32 s86, 4.0
	s_mov_b32 s0, s72
	s_mov_b32 s88, 0x40c00000
	s_mov_b32 s90, 0x41800000
	s_mov_b32 s92, 0x41900000
	s_mov_b32 s94, 0x41a00000
	s_mov_b32 s96, 0x41b00000
	s_mov_b32 s22, 0x42580000
	s_mov_b32 s74, 0x42500000
	s_mov_b32 s76, 0x42480000
	s_mov_b32 s24, 0x42400000
	s_mov_b32 s26, 0x42180000
	s_mov_b32 s72, 0x42100000
	s_mov_b32 s18, 0x42080000
	s_mov_b32 s34, 0x42000000
	v_cmp_eq_u32_e64 s[2:3], 0, v147
	v_lshrrev_b32_e32 v162, 4, v146
	v_mul_u32_u24_e32 v167, 0x810, v9
	v_lshlrev_b32_e32 v168, 4, v161
	v_ashrrev_i32_e32 v139, 31, v138
	v_ashrrev_i32_e32 v141, 31, v140
	v_lshl_add_u64 v[142:143], s[6:7], 0, v[130:131]
	v_add3_u32 v175, v171, s16, v161
	v_add_u32_e32 v176, v4, v5
	v_add_u32_e32 v177, v4, v6
	v_add_u32_e32 v178, v4, v7
	v_add_u32_e32 v179, v4, v8
	v_bfrev_b32_e32 v180, -2
	v_mov_b32_e32 v181, 0x260
	v_mov_b32_e32 v182, 0x3a83126f
	s_mov_b32 s41, 0xc2040000
	s_mov_b32 s43, 0xc0400000
	s_mov_b32 s45, 0xc20c0000
	s_mov_b32 s47, 0xc0a00000
	s_mov_b32 s49, 0xc2140000
	s_mov_b32 s51, 0xc0e00000
	s_mov_b32 s53, 0xc21c0000
	s_mov_b32 s55, 0xc1880000
	s_mov_b32 s57, 0xc2440000
	s_mov_b32 s59, 0xc1980000
	s_mov_b32 s61, 0xc24c0000
	s_mov_b32 s63, 0xc1a80000
	s_mov_b32 s65, 0xc2540000
	s_mov_b32 s67, 0xc1b80000
	s_mov_b32 s83, 0xc25c0000
	s_mov_b32 s85, 0x40400000
	s_mov_b32 s87, 0x40a00000
	s_mov_b32 s89, 0x40e00000
	s_mov_b32 s91, 0x41880000
	s_mov_b32 s93, 0x41980000
	s_mov_b32 s95, 0x41a80000
	s_mov_b32 s97, 0x41b80000
	s_mov_b32 s23, 0x425c0000
	s_mov_b32 s75, 0x42540000
	s_mov_b32 s77, 0x424c0000
	s_mov_b32 s25, 0x42440000
	s_mov_b32 s27, 0x421c0000
	s_mov_b32 s73, 0x42140000
	s_mov_b32 s19, 0x420c0000
	s_mov_b32 s35, 0x42040000
	v_mov_b32_e32 v183, 0x358637bd
	v_lshlrev_b32_e32 v144, 1, v0
	v_mov_b32_e32 v184, 1
	v_mov_b32_e32 v185, 0x9c
	v_add_u32_e32 v186, v11, v10
	v_writelane_b32 v240, s2, 32
	v_cmp_eq_u32_e64 s[6:7], 0, v196
	v_readlane_b32 s1, v241, 38
	v_readlane_b32 s4, v241, 41
	v_readlane_b32 s5, v241, 42
	v_readlane_b32 s8, v241, 45
	v_readlane_b32 s9, v241, 46
	v_readlane_b32 s10, v241, 47
	v_readlane_b32 s11, v241, 48
	v_readlane_b32 s12, v241, 49
	v_readlane_b32 s13, v241, 50
	v_readlane_b32 s14, v241, 51
	v_readlane_b32 s15, v241, 52
	v_writelane_b32 v241, s16, 37
	v_writelane_b32 v240, s3, 33
	s_branch .LBB0_564
